# v7 + static s_setprio 1 for odd hardware wave slots at each phase start
# speedup vs baseline: 1.0640x; 1.0030x over previous
.LBB0_9:
	s_getreg_b32 s0, hwreg(HW_REG_HW_ID, 0, 1)
	s_cmp_eq_u32 s0, 1
	s_cbranch_scc0 .Lprio_skip
	s_setprio 1
